# scan part 1 out^T = V^T P: fragment reads of the active key-pair blocks issued together before the first block, counted LDS waits
# baseline (speedup 1.0000x reference)
.LBB0_669:
	s_or_b64 exec, exec, s[50:51]
	v_and_b32_e32 v3, 64, v230
	v_xor_b32_e32 v1, 16, v230
	v_add_u32_e32 v3, 64, v3
	v_cmp_lt_i32_e32 vcc, v1, v3
	v_xor_b32_e32 v128, 32, v230
	v_add_u32_e32 v214, 0x1000, v196
	v_cndmask_b32_e32 v1, v230, v1, vcc
	v_lshlrev_b32_e32 v1, 2, v1
	ds_bpermute_b32 v1, v1, v2
	v_cmp_lt_i32_e32 vcc, v128, v3
	v_mov_b32_e32 v3, v0
	s_waitcnt lgkmcnt(0)
	v_add_f32_e32 v212, v2, v1
	v_cndmask_b32_e32 v1, v230, v128, vcc
	v_lshlrev_b32_e32 v1, 2, v1
	ds_bpermute_b32 v213, v1, v212
	s_and_b64 vcc, exec, s[16:17]
	s_cbranch_vccz .Lscan_o1_hd
	ds_read2_b64 v[216:219], v196 offset1:4
	ds_read2_b64 v[220:223], v214 offset0:32 offset1:36
	s_and_b64 vcc, exec, s[20:21]
	s_cbranch_vccz .Lscan_o1_hd
	ds_read2_b64 v[226:229], v196 offset0:8 offset1:12
	ds_read2_b64 v[236:239], v214 offset0:40 offset1:44
	s_and_b64 vcc, exec, s[24:25]
	s_cbranch_vccz .Lscan_o1_hd
	ds_read2_b64 v[240:243], v196 offset0:16 offset1:20
	ds_read2_b64 v[244:247], v214 offset0:48 offset1:52
	s_and_b64 vcc, exec, s[28:29]
	s_cbranch_vccz .Lscan_o1_hd
	ds_read2_b64 v[248:251], v196 offset0:24 offset1:28
.Lscan_o1_hd:
	v_mov_b32_e32 v2, v0
	v_mov_b32_e32 v1, v0
	v_mov_b64_e32 v[130:131], v[2:3]
	v_mov_b64_e32 v[134:135], v[2:3]
	v_mov_b64_e32 v[128:129], v[0:1]
	v_mov_b64_e32 v[132:133], v[0:1]
	s_and_saveexec_b64 s[50:51], s[16:17]
	s_cbranch_execz .LBB0_673
	v_cvt_pk_bf16_f32 v100, v100, v101
	v_cvt_pk_bf16_f32 v101, v102, v103
	v_cvt_pk_bf16_f32 v102, v96, v97
	v_cvt_pk_bf16_f32 v103, v98, v99
	s_waitcnt lgkmcnt(1)
	v_mfma_f32_16x16x32_bf16 v[132:135], v[216:219], v[100:103], 0
	s_waitcnt lgkmcnt(0)
	v_mfma_f32_16x16x32_bf16 v[128:131], v[220:223], v[100:103], 0
	s_or_b64 exec, exec, s[50:51]
	s_and_saveexec_b64 s[50:51], s[20:21]
	s_cbranch_execnz .LBB0_674

.LBB0_672:
	v_cvt_pk_bf16_f32 v96, v116, v117
	v_cvt_pk_bf16_f32 v97, v118, v119
	v_cvt_pk_bf16_f32 v98, v112, v113
	v_cvt_pk_bf16_f32 v99, v114, v115
	s_waitcnt lgkmcnt(1)
	s_nop 0
	v_mfma_f32_16x16x32_bf16 v[132:135], v[240:243], v[96:99], v[132:135]
	s_waitcnt lgkmcnt(0)
	v_mfma_f32_16x16x32_bf16 v[128:131], v[244:247], v[96:99], v[128:131]
	s_or_b64 exec, exec, s[50:51]
	s_and_saveexec_b64 s[50:51], s[28:29]
	s_cbranch_execnz .LBB0_676
	s_branch .LBB0_677

.LBB0_674:
	v_cvt_pk_bf16_f32 v96, v108, v109
	v_cvt_pk_bf16_f32 v97, v110, v111
	v_cvt_pk_bf16_f32 v98, v104, v105
	v_cvt_pk_bf16_f32 v99, v106, v107
	s_waitcnt lgkmcnt(1)
	s_nop 0
	v_mfma_f32_16x16x32_bf16 v[132:135], v[226:229], v[96:99], v[132:135]
	s_waitcnt lgkmcnt(0)
	v_mfma_f32_16x16x32_bf16 v[128:131], v[236:239], v[96:99], v[128:131]
	s_or_b64 exec, exec, s[50:51]
	s_and_saveexec_b64 s[50:51], s[24:25]
	s_cbranch_execnz .LBB0_672

.LBB0_676:
	v_cvt_pk_bf16_f32 v96, v124, v125
	v_cvt_pk_bf16_f32 v97, v126, v127
	v_cvt_pk_bf16_f32 v98, v120, v121
	v_cvt_pk_bf16_f32 v99, v122, v123
	s_waitcnt lgkmcnt(0)
	s_nop 0
	v_mfma_f32_16x16x32_bf16 v[132:135], v[248:251], v[96:99], v[132:135]
	ds_read2_b64 v[100:103], v214 offset0:56 offset1:60
	s_waitcnt lgkmcnt(0)
	v_mfma_f32_16x16x32_bf16 v[128:131], v[100:103], v[96:99], v[128:131]
